# layer-0 mlp2 phase: workgroups without a third tile start ~8 us late (free slack), de-synchronising their residual epilogue bursts from the 64 critical workgroups
# speedup vs baseline: 1.0040x; 1.0040x over previous
; #define PG8_BAR __builtin_amdgcn_s_barrier()
;     DEVI bool next(int i, Unit& u) const {
;         const int ti = i / nb; u.pb = i - ti * nb;
;         const long L = (long)ti * G + c;
;         if (L >= nwg) { const int t = (int)(L - nwg); if (t >= tail_units) return false; u.pm = nM + t / tail_nN; u.pn = t % tail_nN; return true; }
;         int wgid = (int)L; { const int q = nwg / NXCD, r = nwg % NXCD, xcd = wgid % NXCD, off = wgid / NXCD; wgid = (xcd < r ? xcd * (q + 1) : r * (q + 1) + (xcd - r) * q) + off; }
;         const int nig = WGM * nN, gid = wgid / nig, fm = gid * WGM, gsz = (nM - fm) < WGM ? (nM - fm) : WGM;
; template <class Epi>
; DEVI void gemm_phase(const int wv, LAS unsigned char* lds, const Gemm g, const Order& S, const Epi& E) {
;     const int tid = opaque_tid(wv), wid = wv, lane = tid & 63, wr = wid >> 2, wc = wid & 3, fr = lane & 15, fq = lane >> 4;
;     const int K = g.K, nt = K / BK;
;     unsigned voffA[2], voffB[2];
; #pragma unroll
;     for (int i = 0; i < 2; ++i) { int R, C; stage_rc(tid * 16 + i * 8192, R, C); const int Rb = Epi::PERM ? ((R & ~31) + perm32(R & 31)) : R;
;         voffA[i] = (unsigned)(R * g.lda + C) * 2u; voffB[i] = (unsigned)(Rb * g.ldb + C) * 2u; }
;     const size_t kstep = (size_t)(BK * 2);
;     const size_t hstepA = (size_t)HALF * g.lda * 2, hstepB = (size_t)HALF * g.ldb * 2;
;     const size_t tstepA = 2 * hstepA, tstepB = 2 * hstepB;
;     const unsigned ldsw = (unsigned)wid * 1024u;
;     const int aoff = lds_byte(wr * 64 + fr, fq * 8), boff = lds_byte(wc * 32 + fr, fq * 8);
;     ...
;     Unit cur, nxt; int ui = 0;
;     if (!S.next(0, cur)) return;
;     f32x4 acc[2][2][4][2];
; #pragma unroll
;     for (int a = 0; a < 2; ++a)
; #pragma unroll
;         for (int b = 0; b < 2; ++b)
; #pragma unroll
;             for (int m = 0; m < 4; ++m)
; #pragma unroll
;                 for (int n = 0; n < 2; ++n) acc[a][b][m][n] = (f32x4){0.f, 0.f, 0.f, 0.f};
;     bf16x8 At[4][2], B0[2][2], B1[2][2];
;     const char* cA = (const char*)g.A + (size_t)cur.pb * g.a_bs + (size_t)cur.pm * tstepA; const char* cB = (const char*)g.Bt + (size_t)cur.pb * g.b_bs + (size_t)cur.pn * tstepB;
;     PG8_STAGE(PG8_SB(0, 0), cB, voffB); PG8_STAGE(PG8_SA(0, 0), cA, voffA); PG8_STAGE(PG8_SB(0, 1), cB + hstepB, voffB); PG8_STAGE(PG8_SA(0, 1), cA + hstepA, voffA);
;     if (wr == 1) PG8_BAR;
;     PG8_WAIT_V(4); PG8_BAR;
.LBB0_1343:
	s_cmp_lt_i32 s18, s26
	s_cselect_b64 s[0:1], -1, 0
	s_cmp_ge_i32 s18, s27
	s_cselect_b64 s[2:3], -1, 0
	s_or_b64 s[0:1], s[0:1], s[2:3]
	s_and_b64 vcc, exec, s[0:1]
	v_readlane_b32 s2, v253, 29
	v_readlane_b32 s3, v253, 30
	s_cbranch_vccnz .LBB0_149
	v_readlane_b32 s1, v253, 35
	s_lshr_b32 s18, s1, 6
	v_readlane_b32 s0, v253, 12
	s_cmp_ge_i32 s0, s18
	v_mbcnt_lo_u32_b32 v8, -1, 0
	v_mbcnt_hi_u32_b32 v8, -1, v8
	s_cbranch_scc1 .LBB0_1359
	v_readlane_b32 vcc_lo, v253, 31
	s_nop 3
	s_cmp_lg_u32 vcc_lo, 0
	s_cbranch_scc1 .Lstg_skip_b
	s_cmp_lt_u32 s0, 64
	s_cbranch_scc1 .Lstg_skip_b
	s_sleep 127
	s_sleep 127
.Lstg_skip_b:
	v_lshl_add_u32 v0, v8, 4, s95
	v_add_u32_e32 v3, 0x2000, v0
	s_waitcnt lgkmcnt(0)
	v_ashrrev_i32_e32 v2, 31, v3
	v_lshrrev_b32_e32 v2, 22, v2
	v_add_u32_e32 v2, v3, v2
	v_ashrrev_i32_e32 v2, 10, v2
	v_lshlrev_b32_e32 v4, 5, v2
	v_and_b32_e32 v5, 32, v4
	v_mul_i32_i24_e32 v4, 0x400, v2
	v_sub_u32_e32 v3, v3, v4
	v_lshrrev_b32_e32 v4, 4, v3
	v_bitop3_b32 v4, v4, v3, 32 bitop3:0x6c
	v_ashrrev_i32_e32 v3, 31, v4
	v_lshrrev_b32_e32 v3, 26, v3
	v_add_u32_e32 v6, v4, v3
	v_ashrrev_i32_e32 v3, 6, v6
	v_and_b32_e32 v6, 0xffc0, v6
	v_sub_u32_e32 v4, v4, v6
	v_lshrrev_b16_e32 v6, 7, v4
	v_and_b32_e32 v6, 1, v6
	v_add_u16_e32 v4, v4, v6
	v_ashrrev_i16_sdwa v4, v197, sext(v4) dst_sel:DWORD dst_unused:UNUSED_PAD src0_sel:DWORD src1_sel:BYTE_0
	v_lshlrev_b32_e32 v6, 3, v2
	v_bfe_i32 v4, v4, 0, 16
	v_and_b32_e32 v6, 0x7fff0, v6
	v_add_u32_e32 v5, v5, v4
	v_add_lshl_u32 v6, v3, v6, 13
	v_lshl_add_u32 v146, v5, 1, v6
	v_ashrrev_i32_e32 v5, 31, v0
	v_lshrrev_b32_e32 v5, 22, v5
	v_add_u32_e32 v5, v0, v5
	v_ashrrev_i32_e32 v5, 10, v5
	v_lshlrev_b32_e32 v6, 5, v5
	v_and_b32_e32 v9, 32, v6
	v_mul_i32_i24_e32 v6, 0x400, v5
	v_sub_u32_e32 v0, v0, v6
	v_lshrrev_b32_e32 v6, 4, v0
	s_lshr_b32 s37, s1, 9
	v_readlane_b32 s0, v252, 60
	s_lshr_b32 s36, s1, 8
	v_bitop3_b32 v0, v6, v0, 32 bitop3:0x6c
	s_or_b32 s0, s37, s0
	v_readlane_b32 s1, v252, 59
	v_ashrrev_i32_e32 v6, 31, v0
	s_mul_i32 s0, s0, s1
	v_readlane_b32 s1, v252, 5
	v_lshrrev_b32_e32 v6, 26, v6
	s_add_i32 s0, s0, s1
	v_add_u32_e32 v7, v0, v6
	s_ashr_i32 s1, s0, 31
	v_ashrrev_i32_e32 v6, 6, v7
	v_and_b32_e32 v7, 0xc0, v7
	s_lshr_b32 s1, s1, 27
	v_sub_u32_e32 v0, v0, v7
	s_add_i32 s1, s0, s1
	v_ashrrev_i16_sdwa v0, v197, sext(v0) dst_sel:DWORD dst_unused:UNUSED_PAD src0_sel:DWORD src1_sel:BYTE_0
	s_ashr_i32 s2, s1, 5
	v_bfe_i32 v7, v0, 0, 16
	s_lshl_b32 s2, s2, 3
	v_add_u32_e32 v0, v9, v7
	v_lshlrev_b32_e32 v9, 3, v5
	s_sub_i32 s3, s36, s2
	v_and_b32_e32 v9, 0x7fff0, v9
	s_min_i32 s3, s3, 8
	v_add_lshl_u32 v9, v6, v9, 13
	s_abs_i32 s5, s3
	v_lshl_add_u32 v0, v0, 1, v9
	v_cvt_f32_u32_e32 v9, s5
	s_sub_i32 s6, 0, s5
	s_andn2_b32 s1, s1, 31
	s_sub_i32 s1, s0, s1
	v_rcp_iflag_f32_e32 v9, v9
	s_abs_i32 s4, s1
	s_xor_b32 s0, s1, s3
	s_ashr_i32 s0, s0, 31
	v_mul_f32_e32 v9, 0x4f7ffffe, v9
	v_cvt_u32_f32_e32 v9, v9
	s_nop 0
	v_readfirstlane_b32 s7, v9
	s_mul_i32 s6, s6, s7
	s_mul_hi_u32 s6, s7, s6
	s_add_i32 s7, s7, s6
	s_mul_hi_u32 s6, s4, s7
	s_mul_i32 s7, s6, s5
	s_sub_i32 s4, s4, s7
	s_add_i32 s7, s6, 1
	s_sub_i32 s8, s4, s5
	s_cmp_ge_u32 s4, s5
	s_cselect_b32 s6, s7, s6
	s_cselect_b32 s4, s8, s4
	s_add_i32 s7, s6, 1
	s_cmp_ge_u32 s4, s5
	s_cselect_b32 s4, s7, s6
	s_xor_b32 s4, s4, s0
	s_sub_i32 s0, s4, s0
	s_mul_i32 s3, s0, s3
	s_sub_i32 s1, s1, s3
	s_add_i32 s12, s2, s1
	s_ashr_i32 s13, s12, 31
	s_ashr_i32 s1, s0, 31
	s_lshl_b64 s[2:3], s[12:13], 21
	s_lshl_b64 s[4:5], s[0:1], 21
	v_readlane_b32 s6, v250, 31
	v_readlane_b32 s7, v250, 32
	s_add_u32 s30, s6, s4
	s_addc_u32 s31, s7, s5
	s_add_i32 s13, s95, 0
	s_add_i32 m0, s13, 0x10000
	v_readlane_b32 s4, v252, 51
	global_load_lds_dwordx4 v0, s[30:31]
	s_add_i32 m0, s13, 0x12000
	v_readlane_b32 s5, v252, 52
	s_add_u32 s28, s4, s2
	global_load_lds_dwordx4 v146, s[30:31]
	s_addc_u32 s29, s5, s3
	s_mov_b32 m0, s13
	s_add_i32 s38, s13, 0x2000
	global_load_lds_dwordx4 v0, s[28:29]
	s_mov_b32 m0, s38
	s_add_u32 s2, s30, 0x100000
	global_load_lds_dwordx4 v146, s[28:29]
	s_addc_u32 s3, s31, 0
	s_add_i32 m0, s13, 0x14000
	s_nop 0
	global_load_lds_dwordx4 v0, s[2:3]
	s_add_i32 m0, s13, 0x16000
	s_nop 0
	global_load_lds_dwordx4 v146, s[2:3]
	s_add_u32 s2, s28, 0x100000
	s_addc_u32 s3, s29, 0
	s_add_i32 s39, s13, 0x4000
	s_mov_b32 m0, s39
	s_add_i32 s40, s13, 0x6000
	global_load_lds_dwordx4 v0, s[2:3]
	s_mov_b32 m0, s40
	s_nop 0
	global_load_lds_dwordx4 v146, s[2:3]
	v_readlane_b32 s2, v252, 10
	v_readlane_b32 s3, v252, 11
	s_andn2_b64 vcc, exec, s[2:3]
	s_cbranch_vccnz .LBB0_1347
	s_barrier
